# v18 plus nt hint on the final y output stores of the last FFN2 epilogue
# speedup vs baseline: 1.0130x; 1.0003x over previous
.LBB0_1851:
	v_mov_b32_e32 v130, v169
	v_mov_b32_e32 v128, v168
	s_lshl_b32 s26, s67, 8
	s_lshl_b32 s27, s68, 8
	s_add_i32 s26, s26, s57
	s_or_b32 s27, s27, s58
	v_lshl_add_u32 v128, v128, 3, s27
	v_add_u32_e32 v164, s26, v130
	v_ashrrev_i32_e32 v129, 31, v128
	v_ashrrev_i32_e32 v165, 31, v164
	v_lshl_add_u64 v[162:163], v[128:129], 1, s[16:17]
	v_lshlrev_b64 v[130:131], 11, v[164:165]
	v_add_u32_e32 v206, 16, v164
	v_lshl_add_u64 v[130:131], v[162:163], 0, v[130:131]
	v_ashrrev_i32_e32 v207, 31, v206
	global_load_dwordx4 v[174:177], v[130:131], off
	global_load_dwordx4 v[178:181], v[130:131], off offset:256
	v_lshlrev_b64 v[130:131], 11, v[206:207]
	v_add_u32_e32 v208, 32, v164
	v_lshl_add_u64 v[130:131], v[162:163], 0, v[130:131]
	v_ashrrev_i32_e32 v209, 31, v208
	s_ashr_i32 s26, s67, 4
	global_load_dwordx4 v[182:185], v[130:131], off
	global_load_dwordx4 v[186:189], v[130:131], off offset:256
	v_lshlrev_b64 v[130:131], 11, v[208:209]
	v_add_u32_e32 v166, 48, v164
	s_mul_hi_i32 s27, s26, 0x6000
	s_mulk_i32 s26, 0x6000
	v_lshl_add_u64 v[130:131], v[162:163], 0, v[130:131]
	v_ashrrev_i32_e32 v167, 31, v166
	s_add_u32 s26, s52, s26
	global_load_dwordx4 v[190:193], v[130:131], off
	global_load_dwordx4 v[194:197], v[130:131], off offset:256
	v_lshlrev_b64 v[130:131], 11, v[166:167]
	s_addc_u32 s27, s53, s27
	v_lshlrev_b64 v[160:161], 2, v[128:129]
	v_lshl_add_u64 v[130:131], v[162:163], 0, v[130:131]
	v_lshl_add_u64 v[128:129], s[26:27], 0, v[160:161]
	global_load_dwordx4 v[198:201], v[130:131], off
	global_load_dwordx4 v[202:205], v[130:131], off offset:256
	global_load_dwordx4 v[140:143], v[128:129], off
	global_load_dwordx4 v[136:139], v[128:129], off offset:16
	global_load_dwordx4 v[132:135], v[128:129], off offset:512
	s_nop 0
	global_load_dwordx4 v[128:131], v[128:129], off offset:528
	v_lshlrev_b64 v[244:245], 12, v[164:165]
	s_and_b64 vcc, exec, s[0:1]
	s_mov_b64 s[0:1], -1
	s_waitcnt vmcnt(0)
	v_lshlrev_b32_e32 v210, 16, v174
	v_and_b32_e32 v211, 0xffff0000, v174
	v_lshlrev_b32_e32 v174, 16, v175
	v_and_b32_e32 v175, 0xffff0000, v175
	v_lshlrev_b32_e32 v214, 16, v178
	v_and_b32_e32 v215, 0xffff0000, v178
	v_lshlrev_b32_e32 v178, 16, v179
	v_and_b32_e32 v179, 0xffff0000, v179
	v_lshlrev_b32_e32 v216, 16, v180
	v_and_b32_e32 v217, 0xffff0000, v180
	v_lshlrev_b32_e32 v212, 16, v176
	v_and_b32_e32 v213, 0xffff0000, v176
	v_lshlrev_b32_e32 v176, 16, v177
	v_and_b32_e32 v177, 0xffff0000, v177
	v_lshlrev_b32_e32 v180, 16, v181
	v_and_b32_e32 v181, 0xffff0000, v181
	v_lshlrev_b32_e32 v218, 16, v182
	v_and_b32_e32 v219, 0xffff0000, v182
	v_lshlrev_b32_e32 v182, 16, v183
	v_pk_fma_f32 v[126:127], v[126:127], v[142:143], v[174:175]
	v_lshl_add_u64 v[174:175], s[36:37], 0, v[244:245]
	v_pk_fma_f32 v[124:125], v[124:125], v[140:141], v[210:211]
	v_lshl_add_u64 v[174:175], v[174:175], 0, v[160:161]
	v_pk_fma_f32 v[118:119], v[118:119], v[134:135], v[178:179]
	v_pk_fma_f32 v[116:117], v[116:117], v[132:133], v[214:215]
	v_pk_fma_f32 v[112:113], v[112:113], v[128:129], v[216:217]
	v_pk_fma_f32 v[122:123], v[122:123], v[138:139], v[176:177]
	v_pk_fma_f32 v[120:121], v[120:121], v[136:137], v[212:213]
	global_store_dwordx4 v[174:175], v[124:127], off nt
	global_store_dwordx4 v[174:175], v[120:123], off offset:16 nt
	v_pk_fma_f32 v[114:115], v[114:115], v[130:131], v[180:181]
	global_store_dwordx4 v[174:175], v[116:119], off offset:512 nt
	global_store_dwordx4 v[174:175], v[112:115], off offset:528 nt
	v_and_b32_e32 v183, 0xffff0000, v183
	v_lshlrev_b32_e32 v222, 16, v186
	v_lshlrev_b64 v[112:113], 12, v[206:207]
	v_and_b32_e32 v223, 0xffff0000, v186
	v_lshlrev_b32_e32 v186, 16, v187
	v_and_b32_e32 v187, 0xffff0000, v187
	v_lshlrev_b32_e32 v224, 16, v188
	v_and_b32_e32 v225, 0xffff0000, v188
	v_lshl_add_u64 v[112:113], s[36:37], 0, v[112:113]
	v_lshlrev_b32_e32 v220, 16, v184
	v_and_b32_e32 v221, 0xffff0000, v184
	v_lshlrev_b32_e32 v184, 16, v185
	v_and_b32_e32 v185, 0xffff0000, v185
	v_lshlrev_b32_e32 v188, 16, v189
	v_and_b32_e32 v189, 0xffff0000, v189
	v_pk_fma_f32 v[110:111], v[110:111], v[142:143], v[182:183]
	v_pk_fma_f32 v[108:109], v[108:109], v[140:141], v[218:219]
	v_lshl_add_u64 v[112:113], v[112:113], 0, v[160:161]
	v_pk_fma_f32 v[102:103], v[102:103], v[134:135], v[186:187]
	v_pk_fma_f32 v[100:101], v[100:101], v[132:133], v[222:223]
	v_pk_fma_f32 v[96:97], v[96:97], v[128:129], v[224:225]
	v_pk_fma_f32 v[106:107], v[106:107], v[138:139], v[184:185]
	v_pk_fma_f32 v[104:105], v[104:105], v[136:137], v[220:221]
	global_store_dwordx4 v[112:113], v[108:111], off nt
	global_store_dwordx4 v[112:113], v[104:107], off offset:16 nt
	v_pk_fma_f32 v[98:99], v[98:99], v[130:131], v[188:189]
	global_store_dwordx4 v[112:113], v[100:103], off offset:512 nt
	global_store_dwordx4 v[112:113], v[96:99], off offset:528 nt
	v_lshlrev_b32_e32 v228, 16, v190
	v_and_b32_e32 v229, 0xffff0000, v190
	v_lshlrev_b64 v[96:97], 12, v[208:209]
	v_lshlrev_b32_e32 v190, 16, v191
	v_and_b32_e32 v191, 0xffff0000, v191
	v_lshlrev_b32_e32 v232, 16, v194
	v_and_b32_e32 v233, 0xffff0000, v194
	v_lshlrev_b32_e32 v194, 16, v195
	v_and_b32_e32 v195, 0xffff0000, v195
	v_lshlrev_b32_e32 v234, 16, v196
	v_and_b32_e32 v235, 0xffff0000, v196
	v_lshl_add_u64 v[96:97], s[36:37], 0, v[96:97]
	v_lshlrev_b32_e32 v230, 16, v192
	v_and_b32_e32 v231, 0xffff0000, v192
	v_lshlrev_b32_e32 v192, 16, v193
	v_and_b32_e32 v193, 0xffff0000, v193
	v_lshlrev_b32_e32 v196, 16, v197
	v_and_b32_e32 v197, 0xffff0000, v197
	v_pk_fma_f32 v[94:95], v[94:95], v[142:143], v[190:191]
	v_pk_fma_f32 v[92:93], v[92:93], v[140:141], v[228:229]
	v_lshl_add_u64 v[96:97], v[96:97], 0, v[160:161]
	v_pk_fma_f32 v[86:87], v[86:87], v[134:135], v[194:195]
	v_pk_fma_f32 v[84:85], v[84:85], v[132:133], v[232:233]
	v_pk_fma_f32 v[80:81], v[80:81], v[128:129], v[234:235]
	v_pk_fma_f32 v[90:91], v[90:91], v[138:139], v[192:193]
	v_pk_fma_f32 v[88:89], v[88:89], v[136:137], v[230:231]
	global_store_dwordx4 v[96:97], v[92:95], off nt
	global_store_dwordx4 v[96:97], v[88:91], off offset:16 nt
	v_pk_fma_f32 v[82:83], v[82:83], v[130:131], v[196:197]
	global_store_dwordx4 v[96:97], v[84:87], off offset:512 nt
	global_store_dwordx4 v[96:97], v[80:83], off offset:528 nt
	v_lshlrev_b32_e32 v236, 16, v198
	v_and_b32_e32 v237, 0xffff0000, v198
	v_lshlrev_b64 v[80:81], 12, v[166:167]
	v_lshlrev_b32_e32 v198, 16, v199
	v_and_b32_e32 v199, 0xffff0000, v199
	v_lshlrev_b32_e32 v240, 16, v202
	v_and_b32_e32 v241, 0xffff0000, v202
	v_lshlrev_b32_e32 v202, 16, v203
	v_and_b32_e32 v203, 0xffff0000, v203
	v_lshlrev_b32_e32 v242, 16, v204
	v_and_b32_e32 v243, 0xffff0000, v204
	v_lshl_add_u64 v[80:81], s[36:37], 0, v[80:81]
	v_add_u32_e32 v98, 0x80, v164
	v_lshlrev_b32_e32 v238, 16, v200
	v_and_b32_e32 v239, 0xffff0000, v200
	v_lshlrev_b32_e32 v200, 16, v201
	v_and_b32_e32 v201, 0xffff0000, v201
	v_lshlrev_b32_e32 v204, 16, v205
	v_and_b32_e32 v205, 0xffff0000, v205
	v_pk_fma_f32 v[78:79], v[78:79], v[142:143], v[198:199]
	v_pk_fma_f32 v[76:77], v[76:77], v[140:141], v[236:237]
	v_lshl_add_u64 v[80:81], v[80:81], 0, v[160:161]
	v_pk_fma_f32 v[70:71], v[70:71], v[134:135], v[202:203]
	v_pk_fma_f32 v[68:69], v[68:69], v[132:133], v[240:241]
	v_pk_fma_f32 v[64:65], v[64:65], v[128:129], v[242:243]
	v_ashrrev_i32_e32 v99, 31, v98
	v_pk_fma_f32 v[74:75], v[74:75], v[138:139], v[200:201]
	v_pk_fma_f32 v[72:73], v[72:73], v[136:137], v[238:239]
	global_store_dwordx4 v[80:81], v[76:79], off nt
	global_store_dwordx4 v[80:81], v[72:75], off offset:16 nt
	v_pk_fma_f32 v[66:67], v[66:67], v[130:131], v[204:205]
	global_store_dwordx4 v[80:81], v[68:71], off offset:512 nt
	global_store_dwordx4 v[80:81], v[64:67], off offset:528 nt
	v_add_u32_e32 v100, 0x90, v164
	v_ashrrev_i32_e32 v101, 31, v100
	v_lshlrev_b64 v[64:65], 11, v[98:99]
	v_lshl_add_u64 v[64:65], v[162:163], 0, v[64:65]
	global_load_dwordx4 v[66:69], v[64:65], off
	global_load_dwordx4 v[70:73], v[64:65], off offset:256
	v_lshlrev_b64 v[64:65], 11, v[100:101]
	v_add_u32_e32 v102, 0xa0, v164
	v_lshl_add_u64 v[64:65], v[162:163], 0, v[64:65]
	v_ashrrev_i32_e32 v103, 31, v102
	global_load_dwordx4 v[74:77], v[64:65], off
	global_load_dwordx4 v[78:81], v[64:65], off offset:256
	v_lshlrev_b64 v[64:65], 11, v[102:103]
	v_lshl_add_u64 v[64:65], v[162:163], 0, v[64:65]
	global_load_dwordx4 v[82:85], v[64:65], off
	global_load_dwordx4 v[86:89], v[64:65], off offset:256
	v_add_u32_e32 v64, 0xb0, v164
	v_ashrrev_i32_e32 v65, 31, v64
	v_lshlrev_b64 v[90:91], 11, v[64:65]
	v_lshl_add_u64 v[94:95], v[162:163], 0, v[90:91]
	global_load_dwordx4 v[90:93], v[94:95], off
	s_nop 0
	global_load_dwordx4 v[94:97], v[94:95], off offset:256
	v_lshlrev_b64 v[98:99], 12, v[98:99]
	s_waitcnt vmcnt(0)
	v_lshlrev_b32_e32 v104, 16, v66
	v_and_b32_e32 v105, 0xffff0000, v66
	v_lshlrev_b32_e32 v66, 16, v67
	v_and_b32_e32 v67, 0xffff0000, v67
	v_lshlrev_b32_e32 v108, 16, v70
	v_and_b32_e32 v109, 0xffff0000, v70
	v_lshlrev_b32_e32 v70, 16, v71
	v_and_b32_e32 v71, 0xffff0000, v71
	v_lshlrev_b32_e32 v110, 16, v72
	v_and_b32_e32 v111, 0xffff0000, v72
	v_pk_fma_f32 v[62:63], v[62:63], v[142:143], v[66:67]
	v_lshl_add_u64 v[66:67], s[36:37], 0, v[98:99]
	v_lshlrev_b32_e32 v106, 16, v68
	v_and_b32_e32 v107, 0xffff0000, v68
	v_lshlrev_b32_e32 v68, 16, v69
	v_and_b32_e32 v69, 0xffff0000, v69
	v_lshlrev_b32_e32 v72, 16, v73
	v_and_b32_e32 v73, 0xffff0000, v73
	v_pk_fma_f32 v[60:61], v[60:61], v[140:141], v[104:105]
	v_lshl_add_u64 v[66:67], v[66:67], 0, v[160:161]
	v_pk_fma_f32 v[54:55], v[54:55], v[134:135], v[70:71]
	v_pk_fma_f32 v[52:53], v[52:53], v[132:133], v[108:109]
	v_pk_fma_f32 v[48:49], v[48:49], v[128:129], v[110:111]
	v_pk_fma_f32 v[58:59], v[58:59], v[138:139], v[68:69]
	v_pk_fma_f32 v[56:57], v[56:57], v[136:137], v[106:107]
	global_store_dwordx4 v[66:67], v[60:63], off nt
	global_store_dwordx4 v[66:67], v[56:59], off offset:16 nt
	v_pk_fma_f32 v[50:51], v[50:51], v[130:131], v[72:73]
	global_store_dwordx4 v[66:67], v[52:55], off offset:512 nt
	global_store_dwordx4 v[66:67], v[48:51], off offset:528 nt
	v_lshlrev_b32_e32 v112, 16, v74
	v_and_b32_e32 v113, 0xffff0000, v74
	v_lshlrev_b64 v[48:49], 12, v[100:101]
	v_lshlrev_b32_e32 v74, 16, v75
	v_and_b32_e32 v75, 0xffff0000, v75
	v_lshlrev_b32_e32 v116, 16, v78
	v_and_b32_e32 v117, 0xffff0000, v78
	v_lshlrev_b32_e32 v78, 16, v79
	v_and_b32_e32 v79, 0xffff0000, v79
	v_lshlrev_b32_e32 v118, 16, v80
	v_and_b32_e32 v119, 0xffff0000, v80
	v_lshl_add_u64 v[48:49], s[36:37], 0, v[48:49]
	v_lshlrev_b32_e32 v114, 16, v76
	v_and_b32_e32 v115, 0xffff0000, v76
	v_lshlrev_b32_e32 v76, 16, v77
	v_and_b32_e32 v77, 0xffff0000, v77
	v_lshlrev_b32_e32 v80, 16, v81
	v_and_b32_e32 v81, 0xffff0000, v81
	v_pk_fma_f32 v[46:47], v[46:47], v[142:143], v[74:75]
	v_pk_fma_f32 v[44:45], v[44:45], v[140:141], v[112:113]
	v_lshl_add_u64 v[48:49], v[48:49], 0, v[160:161]
	v_pk_fma_f32 v[38:39], v[38:39], v[134:135], v[78:79]
	v_pk_fma_f32 v[36:37], v[36:37], v[132:133], v[116:117]
	v_pk_fma_f32 v[32:33], v[32:33], v[128:129], v[118:119]
	v_pk_fma_f32 v[42:43], v[42:43], v[138:139], v[76:77]
	v_pk_fma_f32 v[40:41], v[40:41], v[136:137], v[114:115]
	global_store_dwordx4 v[48:49], v[44:47], off nt
	global_store_dwordx4 v[48:49], v[40:43], off offset:16 nt
	v_pk_fma_f32 v[34:35], v[34:35], v[130:131], v[80:81]
	global_store_dwordx4 v[48:49], v[36:39], off offset:512 nt
	global_store_dwordx4 v[48:49], v[32:35], off offset:528 nt
	v_lshlrev_b32_e32 v120, 16, v82
	v_and_b32_e32 v121, 0xffff0000, v82
	v_lshlrev_b64 v[32:33], 12, v[102:103]
	v_lshlrev_b32_e32 v82, 16, v83
	v_and_b32_e32 v83, 0xffff0000, v83
	v_lshlrev_b32_e32 v124, 16, v86
	v_and_b32_e32 v125, 0xffff0000, v86
	v_lshlrev_b32_e32 v86, 16, v87
	v_and_b32_e32 v87, 0xffff0000, v87
	v_lshlrev_b32_e32 v126, 16, v88
	v_and_b32_e32 v127, 0xffff0000, v88
	v_lshl_add_u64 v[32:33], s[36:37], 0, v[32:33]
	v_lshlrev_b32_e32 v122, 16, v84
	v_and_b32_e32 v123, 0xffff0000, v84
	v_lshlrev_b32_e32 v84, 16, v85
	v_and_b32_e32 v85, 0xffff0000, v85
	v_lshlrev_b32_e32 v88, 16, v89
	v_and_b32_e32 v89, 0xffff0000, v89
	v_pk_fma_f32 v[30:31], v[30:31], v[142:143], v[82:83]
	v_pk_fma_f32 v[28:29], v[28:29], v[140:141], v[120:121]
	v_lshl_add_u64 v[32:33], v[32:33], 0, v[160:161]
	v_pk_fma_f32 v[22:23], v[22:23], v[134:135], v[86:87]
	v_pk_fma_f32 v[20:21], v[20:21], v[132:133], v[124:125]
	v_pk_fma_f32 v[16:17], v[16:17], v[128:129], v[126:127]
	v_pk_fma_f32 v[26:27], v[26:27], v[138:139], v[84:85]
	v_pk_fma_f32 v[24:25], v[24:25], v[136:137], v[122:123]
	global_store_dwordx4 v[32:33], v[28:31], off nt
	global_store_dwordx4 v[32:33], v[24:27], off offset:16 nt
	v_pk_fma_f32 v[18:19], v[18:19], v[130:131], v[88:89]
	global_store_dwordx4 v[32:33], v[20:23], off offset:512 nt
	global_store_dwordx4 v[32:33], v[16:19], off offset:528 nt
	v_lshlrev_b32_e32 v162, 16, v90
	v_and_b32_e32 v163, 0xffff0000, v90
	v_lshlrev_b64 v[16:17], 12, v[64:65]
	v_lshlrev_b32_e32 v90, 16, v91
	v_and_b32_e32 v91, 0xffff0000, v91
	v_lshlrev_b32_e32 v166, 16, v94
	v_and_b32_e32 v167, 0xffff0000, v94
	v_lshlrev_b32_e32 v94, 16, v95
	v_and_b32_e32 v95, 0xffff0000, v95
	v_lshl_add_u64 v[16:17], s[36:37], 0, v[16:17]
	v_lshlrev_b32_e32 v164, 16, v92
	v_and_b32_e32 v165, 0xffff0000, v92
	v_lshlrev_b32_e32 v92, 16, v93
	v_and_b32_e32 v93, 0xffff0000, v93
	v_lshlrev_b32_e32 v174, 16, v96
	v_and_b32_e32 v175, 0xffff0000, v96
	v_lshlrev_b32_e32 v96, 16, v97
	v_and_b32_e32 v97, 0xffff0000, v97
	v_pk_fma_f32 v[14:15], v[14:15], v[142:143], v[90:91]
	v_pk_fma_f32 v[12:13], v[12:13], v[140:141], v[162:163]
	v_lshl_add_u64 v[16:17], v[16:17], 0, v[160:161]
	v_pk_fma_f32 v[6:7], v[6:7], v[134:135], v[94:95]
	v_pk_fma_f32 v[4:5], v[4:5], v[132:133], v[166:167]
	v_pk_fma_f32 v[10:11], v[10:11], v[138:139], v[92:93]
	v_pk_fma_f32 v[8:9], v[8:9], v[136:137], v[164:165]
	global_store_dwordx4 v[16:17], v[12:15], off nt
	global_store_dwordx4 v[16:17], v[8:11], off offset:16 nt
	v_pk_fma_f32 v[2:3], v[2:3], v[130:131], v[96:97]
	v_pk_fma_f32 v[0:1], v[0:1], v[128:129], v[174:175]
	global_store_dwordx4 v[16:17], v[4:7], off offset:512 nt
	global_store_dwordx4 v[16:17], v[0:3], off offset:528 nt
	s_cbranch_vccnz .LBB0_1835
	s_andn2_b64 vcc, exec, s[14:15]
	s_cbranch_vccnz .LBB0_1834
	s_barrier
	s_branch .LBB0_1834
